# LRU: fold bias add and -log2e scale into one v_fmamk (pre-scaled biases), fold sp scale: -48 VALU per chunk
# baseline (speedup 1.0000x reference)
; __device__ __forceinline__ unsigned cvt_pk_bf16(float lo, float hi) { unsigned r; asm volatile("v_cvt_pk_bf16_f32 %0, %1, %2" : "=v"(r) : "v"(lo), "v"(hi)); return r; }
; __device__ __forceinline__ float bflo(unsigned w) { return __uint_as_float(w << 16); }
; __device__ __forceinline__ float bfhi(unsigned w) { return __uint_as_float(w & 0xffff0000u); }
; __device__ void lru_fused_phase(const int bid, const int nblk, bf16_t* __restrict__ U, bf16_t* __restrict__ HF, const bf16_t* __restrict__ Wg, const float* __restrict__ cw, const float* __restrict__ cb, ...
;     ...
;             const float ba = b_a[e * DRNN + ch], bi_ = b_i[e * DRNN + ch], sp = c8sp[e * DRNN + ch];
;             float hs = 0.f;
;             unsigned xr[11];
;             {
;                 const int k = e == 0 ? 0 : 31; const int p0 = 64 * k + 8 * wid - 2;
; #pragma unroll
;                 for (int i = 0; i < 11; ++i) { const int pos = p0 + i; xr[i] = (pos >= 0 && pos < SEQ) ? *(const unsigned*)(recp + (long)pos * (2 * DRNN)) : 0u; }
; #pragma unroll
;                 for (int r = 0; r < 8; ++r) {
;                     const float c0 = wb[0] + w0[0] * bflo(xr[r]) + w1[0] * bflo(xr[r + 1]) + w2[0] * bflo(xr[r + 2]) + w3[0] * bflo(xr[r + 3]);
;                     const float c1 = wb[1] + w0[1] * bfhi(xr[r]) + w1[1] * bfhi(xr[r + 1]) + w2[1] * bfhi(xr[r + 2]) + w3[1] * bfhi(xr[r + 3]);
;                     *(unsigned*)(smem + (8 * wid + r) * RS + lane * 4) = cvt_pk_bf16(c0, c1);
;                 }
;             }
;             __syncthreads();
.LBB0_91:
	s_or_b64 exec, exec, s[2:3]
	s_waitcnt vmcnt(0)
	v_mul_f32_e32 v157, 0xbfb8aa3b, v82
	v_mul_f32_e32 v127, 0xbfb8aa3b, v83
	v_mul_f32_e32 v153, 0xbfb8aa3b, v86
	v_lshlrev_b32_e32 v10, 16, v87
	v_fma_f32 v10, v48, v10, v56
	v_lshlrev_b32_e32 v36, 16, v88
	v_and_b32_e32 v39, 0xffff0000, v87
	v_fmac_f32_e32 v10, v50, v36
	v_lshlrev_b32_e32 v37, 16, v89
	v_fma_f32 v39, v49, v39, v57
	v_and_b32_e32 v40, 0xffff0000, v88
	v_fmac_f32_e32 v10, v52, v37
	v_lshlrev_b32_e32 v38, 16, v90
	v_fmac_f32_e32 v39, v51, v40
	v_and_b32_e32 v41, 0xffff0000, v89
	v_fmac_f32_e32 v10, v54, v38
	v_fmac_f32_e32 v39, v53, v41
	v_and_b32_e32 v42, 0xffff0000, v90
	v_fmac_f32_e32 v39, v55, v42
	v_cvt_pk_bf16_f32 v10, v10, v39
	ds_write_b32 v75, v10
	v_fma_f32 v10, v48, v36, v56
	v_fmac_f32_e32 v10, v50, v37
	v_fma_f32 v39, v49, v40, v57
	v_fmac_f32_e32 v10, v52, v38
	v_lshlrev_b32_e32 v36, 16, v92
	v_fmac_f32_e32 v39, v51, v41
	v_fmac_f32_e32 v10, v54, v36
	v_fmac_f32_e32 v39, v53, v42
	v_and_b32_e32 v40, 0xffff0000, v92
	v_fmac_f32_e32 v39, v55, v40
	v_cvt_pk_bf16_f32 v10, v10, v39
	ds_write_b32 v75, v10 offset:272
	v_fma_f32 v10, v48, v37, v56
	v_fmac_f32_e32 v10, v50, v38
	v_fma_f32 v39, v49, v41, v57
	v_fmac_f32_e32 v10, v52, v36
	v_lshlrev_b32_e32 v37, 16, v93
	v_fmac_f32_e32 v39, v51, v42
	v_fmac_f32_e32 v10, v54, v37
	v_fmac_f32_e32 v39, v53, v40
	v_and_b32_e32 v41, 0xffff0000, v93
	v_fmac_f32_e32 v39, v55, v41
	v_cvt_pk_bf16_f32 v10, v10, v39
	ds_write_b32 v75, v10 offset:544
	v_fma_f32 v10, v48, v38, v56
	v_fmac_f32_e32 v10, v50, v36
	v_fma_f32 v39, v49, v42, v57
	v_fmac_f32_e32 v10, v52, v37
	v_lshlrev_b32_e32 v38, 16, v94
	v_fmac_f32_e32 v39, v51, v40
	v_fmac_f32_e32 v10, v54, v38
	v_fmac_f32_e32 v39, v53, v41
	v_and_b32_e32 v42, 0xffff0000, v94
	v_fmac_f32_e32 v39, v55, v42
	v_cvt_pk_bf16_f32 v10, v10, v39
	ds_write_b32 v75, v10 offset:816
	v_fma_f32 v10, v48, v36, v56
	v_fmac_f32_e32 v10, v50, v37
	v_fma_f32 v39, v49, v40, v57
	v_fmac_f32_e32 v10, v52, v38
	v_lshlrev_b32_e32 v36, 16, v95
	v_fmac_f32_e32 v39, v51, v41
	v_fmac_f32_e32 v10, v54, v36
	v_fmac_f32_e32 v39, v53, v42
	v_and_b32_e32 v40, 0xffff0000, v95
	v_fmac_f32_e32 v39, v55, v40
	v_cvt_pk_bf16_f32 v10, v10, v39
	ds_write_b32 v75, v10 offset:1088
	v_fma_f32 v10, v48, v37, v56
	v_fmac_f32_e32 v10, v50, v38
	v_fma_f32 v39, v49, v41, v57
	v_fmac_f32_e32 v10, v52, v36
	v_lshlrev_b32_e32 v37, 16, v96
	v_fmac_f32_e32 v39, v51, v42
	v_fmac_f32_e32 v10, v54, v37
	v_fmac_f32_e32 v39, v53, v40
	v_and_b32_e32 v41, 0xffff0000, v96
	v_fmac_f32_e32 v39, v55, v41
	v_cvt_pk_bf16_f32 v10, v10, v39
	ds_write_b32 v75, v10 offset:1360
	v_fma_f32 v10, v48, v38, v56
	v_fmac_f32_e32 v10, v50, v36
	v_fma_f32 v39, v49, v42, v57
	v_fmac_f32_e32 v10, v52, v37
	v_lshlrev_b32_e32 v38, 16, v97
	v_fmac_f32_e32 v39, v51, v40
	v_fmac_f32_e32 v10, v54, v38
	v_fmac_f32_e32 v39, v53, v41
	v_and_b32_e32 v42, 0xffff0000, v97
	v_fmac_f32_e32 v39, v55, v42
	v_cvt_pk_bf16_f32 v10, v10, v39
	ds_write_b32 v75, v10 offset:1632
	v_fma_f32 v10, v48, v36, v56
	v_fmac_f32_e32 v10, v50, v37
	v_fmac_f32_e32 v10, v52, v38
	v_lshlrev_b32_e32 v36, 16, v103
	v_fmac_f32_e32 v10, v54, v36
	v_fma_f32 v36, v49, v40, v57
	s_xor_b64 s[64:65], s[60:61], -1
	v_fmac_f32_e32 v36, v51, v41
	v_fmac_f32_e32 v36, v53, v42
	v_and_b32_e32 v37, 0xffff0000, v103
	s_and_b64 s[2:3], s[60:61], exec
	v_fmac_f32_e32 v36, v55, v37
	v_cvt_pk_bf16_f32 v10, v10, v36
	s_cselect_b32 s70, 0, 48
	ds_write_b32 v75, v10 offset:1904
	v_or_b32_e32 v10, s70, v47
	v_mul_u32_u24_e32 v98, 0x110, v10
	v_or_b32_e32 v10, s70, v46
	v_mul_u32_u24_e32 v99, 0x110, v10
	v_or_b32_e32 v100, 64, v76
	v_or_b32_e32 v101, 0x80, v76
	v_or_b32_e32 v102, 0xc0, v76
	v_mov_b32_e32 v105, 0
	s_mov_b32 s71, 30
	s_mov_b32 s72, 1
	s_waitcnt lgkmcnt(0)
	s_barrier
	s_branch .LBB0_93

; __device__ __forceinline__ float bf2f(bf16_t b) { return __uint_as_float(((unsigned)b) << 16); }
; __device__ __forceinline__ float sigmoidf(float z) { return __builtin_amdgcn_rcpf(1.0f + __expf(-z)); }
; __device__ void lru_fused_phase(const int bid, const int nblk, bf16_t* __restrict__ U, bf16_t* __restrict__ HF, const bf16_t* __restrict__ Wg, const float* __restrict__ cw, const float* __restrict__ cb, ...
;     ...
;                     for (int s = 0; s < 4; ++s) {
;                         const bf16x8 af = *(const bf16x8*)(buf + (16 * rt + fr) * RS + (32 * s + 8 * fq) * 2);
;                         za = __builtin_amdgcn_mfma_f32_16x16x32_bf16(af, Bf[0][s], za, 0, 0, 0);
;                         zi = __builtin_amdgcn_mfma_f32_16x16x32_bf16(af, Bf[1][s], zi, 0, 0, 0);
;                     }
;                     float av[4], bv[4];
; #pragma unroll
;                     for (int j = 0; j < 4; ++j) {
;                         const float c = bf2f(*(const unsigned short*)(buf + (16 * rt + 4 * fq + j) * RS + chl * 2));
;                         const float r = sigmoidf(za[j] + ba), ig = sigmoidf(zi[j] + bi_);
;                         const float la = -sp * r;
;                         av[j] = __expf(la);
;                         bv[j] = __builtin_sqrtf(fmaxf(1.0f - av[j] * av[j], 0.f)) * ig * c;
;                     }
.LBB0_119:
	s_bitcmp1_b32 s2, 0
	s_cselect_b32 s2, 0x4400, 0
	s_add_i32 s2, s2, 0
	v_add_u32_e32 v104, s2, v8
	v_add_u32_e32 v106, v104, v98
	ds_read_b128 v[36:39], v106
	ds_read_b128 v[108:111], v106 offset:64
	v_add_u32_e32 v10, s2, v74
	s_mov_b64 s[2:3], -1
	s_waitcnt lgkmcnt(1)
	v_mfma_f32_16x16x32_bf16 v[40:43], v[36:39], v[0:3], 0
	v_mfma_f32_16x16x32_bf16 v[36:39], v[36:39], v[20:23], 0
	s_waitcnt lgkmcnt(0)
	v_mfma_f32_16x16x32_bf16 v[40:43], v[108:111], v[4:7], v[40:43]
	v_mfma_f32_16x16x32_bf16 v[36:39], v[108:111], v[24:27], v[36:39]
	ds_read_b128 v[108:111], v106 offset:128
	s_waitcnt lgkmcnt(0)
	v_mfma_f32_16x16x32_bf16 v[40:43], v[108:111], v[12:15], v[40:43]
	v_mfma_f32_16x16x32_bf16 v[36:39], v[108:111], v[28:31], v[36:39]
	ds_read_b128 v[108:111], v106 offset:192
	v_add_u32_e32 v106, v10, v99
	s_waitcnt lgkmcnt(0)
	v_mfma_f32_16x16x32_bf16 v[40:43], v[108:111], v[16:19], v[40:43]
	s_nop 7
	v_fmamk_f32 v40, v40, 0xbfb8aa3b, v157
	v_mfma_f32_16x16x32_bf16 v[36:39], v[108:111], v[32:35], v[36:39]
	v_or_b32_e32 v152, s70, v47
	v_xor_b32_e32 v152, 16, v152
	v_mad_u32_u24 v152, v152, s35, v104
	ds_read_b128 v[128:131], v152
	ds_read_b128 v[132:135], v152 offset:64
	ds_read_b128 v[136:139], v152 offset:128
	ds_read_b128 v[140:143], v152 offset:192
	v_exp_f32_e32 v40, v40
	v_fmamk_f32 v41, v41, 0xbfb8aa3b, v157
	v_exp_f32_e32 v41, v41
	s_nop 2
	v_fmamk_f32 v36, v36, 0xbfb8aa3b, v127
	v_add_f32_e32 v40, 1.0, v40
	v_exp_f32_e32 v36, v36
	v_rcp_f32_e32 v40, v40
	v_fmamk_f32 v37, v37, 0xbfb8aa3b, v127
	v_add_f32_e32 v36, 1.0, v36
	v_rcp_f32_e32 v109, v36
	v_mul_f32_e32 v36, v40, v153
	v_exp_f32_e32 v36, v36
	v_add_f32_e32 v41, 1.0, v41
	v_exp_f32_e32 v37, v37
	v_rcp_f32_e32 v41, v41
	v_fma_f32 v40, -v36, v36, 1.0
	v_max_f32_e32 v40, 0, v40
	v_add_f32_e32 v37, 1.0, v37
	v_sqrt_f32_e32 v40, v40
	s_nop 0
	v_fmamk_f32 v42, v42, 0xbfb8aa3b, v157
	v_exp_f32_e32 v42, v42
	v_fmamk_f32 v38, v38, 0xbfb8aa3b, v127
	v_add_f32_e32 v42, 1.0, v42
	v_exp_f32_e32 v38, v38
	v_rcp_f32_e32 v42, v42
	v_mul_f32_e32 v40, v109, v40
	v_rcp_f32_e32 v109, v37
	v_mul_f32_e32 v37, v41, v153
	v_exp_f32_e32 v37, v37
	v_add_f32_e32 v38, 1.0, v38
	ds_read_u16 v108, v106
	v_fmamk_f32 v43, v43, 0xbfb8aa3b, v157
	v_fma_f32 v41, -v37, v37, 1.0
	v_max_f32_e32 v41, 0, v41
	s_waitcnt lgkmcnt(0)
	v_lshlrev_b32_e32 v108, 16, v108
	v_sqrt_f32_e32 v41, v41
	s_nop 0
	v_mul_f32_e32 v40, v40, v108
	ds_read_u16 v108, v106 offset:272
	v_exp_f32_e32 v43, v43
	s_waitcnt lgkmcnt(0)
	v_lshlrev_b32_e32 v108, 16, v108
	v_fmamk_f32 v39, v39, 0xbfb8aa3b, v127
	s_waitcnt lgkmcnt(0)
	v_mfma_f32_16x16x32_bf16 v[144:147], v[128:131], v[0:3], 0
	v_mfma_f32_16x16x32_bf16 v[148:151], v[128:131], v[20:23], 0
	v_mfma_f32_16x16x32_bf16 v[144:147], v[132:135], v[4:7], v[144:147]
	v_mfma_f32_16x16x32_bf16 v[148:151], v[132:135], v[24:27], v[148:151]
	v_mfma_f32_16x16x32_bf16 v[144:147], v[136:139], v[12:15], v[144:147]
	v_mfma_f32_16x16x32_bf16 v[148:151], v[136:139], v[28:31], v[148:151]
	v_mfma_f32_16x16x32_bf16 v[144:147], v[140:143], v[16:19], v[144:147]
	v_mfma_f32_16x16x32_bf16 v[148:151], v[140:143], v[32:35], v[148:151]
	v_add_f32_e32 v43, 1.0, v43
	v_mul_f32_e32 v41, v109, v41
	v_rcp_f32_e32 v109, v38
	v_mul_f32_e32 v38, v42, v153
	v_exp_f32_e32 v38, v38
	v_mul_f32_e32 v41, v41, v108
	ds_read_u16 v108, v106 offset:544
	v_exp_f32_e32 v39, v39
	v_fma_f32 v42, -v38, v38, 1.0
	v_max_f32_e32 v42, 0, v42
	v_rcp_f32_e32 v43, v43
	v_sqrt_f32_e32 v42, v42
	s_nop 0
	s_waitcnt lgkmcnt(0)
	v_lshlrev_b32_e32 v108, 16, v108
	v_add_f32_e32 v39, 1.0, v39
	ds_read_u16 v106, v106 offset:816
	s_waitcnt lgkmcnt(0)
	v_lshlrev_b32_e32 v106, 16, v106
	s_nop 1
	s_nop 1
	v_mul_f32_e32 v42, v109, v42
	v_mul_f32_e32 v42, v42, v108
	v_rcp_f32_e32 v108, v39
	v_mul_f32_e32 v39, v43, v153
	v_exp_f32_e32 v39, v39
	s_nop 0
	v_fma_f32 v43, -v39, v39, 1.0
	v_max_f32_e32 v43, 0, v43
	s_nop 0
	v_sqrt_f32_e32 v43, v43
	s_nop 0
	s_nop 0
	s_nop 0
	s_nop 1
	s_nop 1
	v_mul_f32_e32 v43, v108, v43
	v_mul_f32_e32 v43, v43, v106
	s_and_b64 vcc, exec, s[64:65]
	s_cbranch_vccz .LBB0_121
	v_fma_f32 v108, v38, v43, v42
	v_mul_f32_e32 v109, v38, v39
	v_fma_f32 v111, v37, v108, v41
	v_mul_f32_e32 v110, v37, v109
	v_fma_f32 v112, v36, v111, v40
	v_mul_f32_e32 v106, v36, v110
	s_mov_b64 s[2:3], 0

; __device__ __forceinline__ float bf2f(bf16_t b) { return __uint_as_float(((unsigned)b) << 16); }
; __device__ __forceinline__ float sigmoidf(float z) { return __builtin_amdgcn_rcpf(1.0f + __expf(-z)); }
; __device__ void lru_fused_phase(const int bid, const int nblk, bf16_t* __restrict__ U, bf16_t* __restrict__ HF, const bf16_t* __restrict__ Wg, const float* __restrict__ cw, const float* __restrict__ cb, ...
;     ...
;                     for (int s = 0; s < 4; ++s) {
;                         const bf16x8 af = *(const bf16x8*)(buf + (16 * rt + fr) * RS + (32 * s + 8 * fq) * 2);
;                         za = __builtin_amdgcn_mfma_f32_16x16x32_bf16(af, Bf[0][s], za, 0, 0, 0);
;                         zi = __builtin_amdgcn_mfma_f32_16x16x32_bf16(af, Bf[1][s], zi, 0, 0, 0);
;                     }
;                     float av[4], bv[4];
; #pragma unroll
;                     for (int j = 0; j < 4; ++j) {
;                         const float c = bf2f(*(const unsigned short*)(buf + (16 * rt + 4 * fq + j) * RS + chl * 2));
;                         const float r = sigmoidf(za[j] + ba), ig = sigmoidf(zi[j] + bi_);
;                         const float la = -sp * r;
;                         av[j] = __expf(la);
;                         bv[j] = __builtin_sqrtf(fmaxf(1.0f - av[j] * av[j], 0.f)) * ig * c;
;                     }
.LBB0_142:
	s_mov_b64 s[2:3], -1
	s_waitcnt lgkmcnt(1)
	s_waitcnt lgkmcnt(0)
	s_waitcnt lgkmcnt(0)
	v_or_b32_e32 v105, s38, v46
	v_mad_u32_u24 v105, v105, s35, v10
	s_waitcnt lgkmcnt(0)
	v_or_b32_e32 v152, s70, v47
	v_xor_b32_e32 v152, 32, v152
	v_mad_u32_u24 v152, v152, s35, v104
	ds_read_b128 v[128:131], v152
	ds_read_b128 v[132:135], v152 offset:64
	ds_read_b128 v[136:139], v152 offset:128
	ds_read_b128 v[140:143], v152 offset:192
	v_fmamk_f32 v40, v144, 0xbfb8aa3b, v157
	v_exp_f32_e32 v40, v40
	v_fmamk_f32 v41, v145, 0xbfb8aa3b, v157
	v_exp_f32_e32 v41, v41
	s_nop 2
	v_fmamk_f32 v36, v148, 0xbfb8aa3b, v127
	v_add_f32_e32 v40, 1.0, v40
	v_exp_f32_e32 v36, v36
	v_rcp_f32_e32 v40, v40
	v_fmamk_f32 v37, v149, 0xbfb8aa3b, v127
	v_add_f32_e32 v36, 1.0, v36
	v_rcp_f32_e32 v109, v36
	v_mul_f32_e32 v36, v40, v153
	v_exp_f32_e32 v36, v36
	v_add_f32_e32 v41, 1.0, v41
	v_exp_f32_e32 v37, v37
	v_rcp_f32_e32 v41, v41
	v_fma_f32 v40, -v36, v36, 1.0
	v_max_f32_e32 v40, 0, v40
	v_add_f32_e32 v37, 1.0, v37
	v_sqrt_f32_e32 v40, v40
	s_nop 0
	v_fmamk_f32 v42, v146, 0xbfb8aa3b, v157
	v_exp_f32_e32 v42, v42
	v_fmamk_f32 v38, v150, 0xbfb8aa3b, v127
	v_add_f32_e32 v42, 1.0, v42
	v_exp_f32_e32 v38, v38
	v_rcp_f32_e32 v42, v42
	v_mul_f32_e32 v40, v109, v40
	v_rcp_f32_e32 v109, v37
	v_mul_f32_e32 v37, v41, v153
	v_exp_f32_e32 v37, v37
	v_add_f32_e32 v38, 1.0, v38
	ds_read_u16 v108, v105
	v_fmamk_f32 v43, v147, 0xbfb8aa3b, v157
	v_fma_f32 v41, -v37, v37, 1.0
	v_max_f32_e32 v41, 0, v41
	s_waitcnt lgkmcnt(0)
	v_lshlrev_b32_e32 v108, 16, v108
	v_sqrt_f32_e32 v41, v41
	s_nop 0
	v_mul_f32_e32 v40, v40, v108
	ds_read_u16 v108, v105 offset:272
	v_exp_f32_e32 v43, v43
	s_waitcnt lgkmcnt(0)
	v_lshlrev_b32_e32 v108, 16, v108
	v_fmamk_f32 v39, v151, 0xbfb8aa3b, v127
	s_waitcnt lgkmcnt(0)
	v_mfma_f32_16x16x32_bf16 v[144:147], v[128:131], v[0:3], 0
	v_mfma_f32_16x16x32_bf16 v[148:151], v[128:131], v[20:23], 0
	v_mfma_f32_16x16x32_bf16 v[144:147], v[132:135], v[4:7], v[144:147]
	v_mfma_f32_16x16x32_bf16 v[148:151], v[132:135], v[24:27], v[148:151]
	v_mfma_f32_16x16x32_bf16 v[144:147], v[136:139], v[12:15], v[144:147]
	v_mfma_f32_16x16x32_bf16 v[148:151], v[136:139], v[28:31], v[148:151]
	v_mfma_f32_16x16x32_bf16 v[144:147], v[140:143], v[16:19], v[144:147]
	v_mfma_f32_16x16x32_bf16 v[148:151], v[140:143], v[32:35], v[148:151]
	v_add_f32_e32 v43, 1.0, v43
	v_mul_f32_e32 v41, v109, v41
	v_rcp_f32_e32 v109, v38
	v_mul_f32_e32 v38, v42, v153
	v_exp_f32_e32 v38, v38
	v_mul_f32_e32 v41, v41, v108
	ds_read_u16 v108, v105 offset:544
	v_exp_f32_e32 v39, v39
	v_fma_f32 v42, -v38, v38, 1.0
	v_max_f32_e32 v42, 0, v42
	v_rcp_f32_e32 v43, v43
	v_sqrt_f32_e32 v42, v42
	s_nop 0
	s_waitcnt lgkmcnt(0)
	v_lshlrev_b32_e32 v108, 16, v108
	v_add_f32_e32 v39, 1.0, v39
	ds_read_u16 v105, v105 offset:816
	s_waitcnt lgkmcnt(0)
	v_lshlrev_b32_e32 v105, 16, v105
	s_nop 1
	s_nop 1
	v_mul_f32_e32 v42, v109, v42
	v_mul_f32_e32 v42, v42, v108
	v_rcp_f32_e32 v108, v39
	v_mul_f32_e32 v39, v43, v153
	v_exp_f32_e32 v39, v39
	s_nop 0
	v_fma_f32 v43, -v39, v39, 1.0
	v_max_f32_e32 v43, 0, v43
	s_nop 0
	v_sqrt_f32_e32 v43, v43
	s_nop 0
	s_nop 0
	s_nop 0
	s_nop 1
	s_nop 1
	v_mul_f32_e32 v43, v108, v43
	v_mul_f32_e32 v43, v43, v105
	s_and_b64 vcc, exec, s[8:9]
	s_cbranch_vccnz .LBB0_144
	v_fma_f32 v108, v38, v43, v42
	v_mul_f32_e32 v109, v38, v39
	v_fma_f32 v111, v37, v108, v41
	v_mul_f32_e32 v110, v37, v109
	v_fma_f32 v112, v36, v111, v40
	v_mul_f32_e32 v105, v36, v110
	s_mov_b64 s[2:3], 0

; __device__ __forceinline__ float bf2f(bf16_t b) { return __uint_as_float(((unsigned)b) << 16); }
; __device__ __forceinline__ float sigmoidf(float z) { return __builtin_amdgcn_rcpf(1.0f + __expf(-z)); }
; __device__ void lru_fused_phase(const int bid, const int nblk, bf16_t* __restrict__ U, bf16_t* __restrict__ HF, const bf16_t* __restrict__ Wg, const float* __restrict__ cw, const float* __restrict__ cb, ...
;     ...
;                     for (int s = 0; s < 4; ++s) {
;                         const bf16x8 af = *(const bf16x8*)(buf + (16 * rt + fr) * RS + (32 * s + 8 * fq) * 2);
;                         za = __builtin_amdgcn_mfma_f32_16x16x32_bf16(af, Bf[0][s], za, 0, 0, 0);
;                         zi = __builtin_amdgcn_mfma_f32_16x16x32_bf16(af, Bf[1][s], zi, 0, 0, 0);
;                     }
;                     float av[4], bv[4];
; #pragma unroll
;                     for (int j = 0; j < 4; ++j) {
;                         const float c = bf2f(*(const unsigned short*)(buf + (16 * rt + 4 * fq + j) * RS + chl * 2));
;                         const float r = sigmoidf(za[j] + ba), ig = sigmoidf(zi[j] + bi_);
;                         const float la = -sp * r;
;                         av[j] = __expf(la);
;                         bv[j] = __builtin_sqrtf(fmaxf(1.0f - av[j] * av[j], 0.f)) * ig * c;
;                     }
.LBB0_165:
	s_mov_b64 s[2:3], -1
	s_waitcnt lgkmcnt(1)
	s_waitcnt lgkmcnt(0)
	s_waitcnt lgkmcnt(0)
	v_or_b32_e32 v106, s38, v46
	v_mad_u32_u24 v106, v106, s35, v10
	s_waitcnt lgkmcnt(0)
	v_or_b32_e32 v152, s70, v47
	v_xor_b32_e32 v152, 48, v152
	v_mad_u32_u24 v152, v152, s35, v104
	ds_read_b128 v[128:131], v152
	ds_read_b128 v[132:135], v152 offset:64
	ds_read_b128 v[136:139], v152 offset:128
	ds_read_b128 v[140:143], v152 offset:192
	v_fmamk_f32 v40, v144, 0xbfb8aa3b, v157
	v_exp_f32_e32 v40, v40
	v_fmamk_f32 v41, v145, 0xbfb8aa3b, v157
	v_exp_f32_e32 v41, v41
	s_nop 2
	v_fmamk_f32 v36, v148, 0xbfb8aa3b, v127
	v_add_f32_e32 v40, 1.0, v40
	v_exp_f32_e32 v36, v36
	v_rcp_f32_e32 v40, v40
	v_fmamk_f32 v37, v149, 0xbfb8aa3b, v127
	v_add_f32_e32 v36, 1.0, v36
	v_rcp_f32_e32 v109, v36
	v_mul_f32_e32 v36, v40, v153
	v_exp_f32_e32 v36, v36
	v_add_f32_e32 v41, 1.0, v41
	v_exp_f32_e32 v37, v37
	v_rcp_f32_e32 v41, v41
	v_fma_f32 v40, -v36, v36, 1.0
	v_max_f32_e32 v40, 0, v40
	v_add_f32_e32 v37, 1.0, v37
	v_sqrt_f32_e32 v40, v40
	s_nop 0
	v_fmamk_f32 v42, v146, 0xbfb8aa3b, v157
	v_exp_f32_e32 v42, v42
	v_fmamk_f32 v38, v150, 0xbfb8aa3b, v127
	v_add_f32_e32 v42, 1.0, v42
	v_exp_f32_e32 v38, v38
	v_rcp_f32_e32 v42, v42
	v_mul_f32_e32 v40, v109, v40
	v_rcp_f32_e32 v109, v37
	v_mul_f32_e32 v37, v41, v153
	v_exp_f32_e32 v37, v37
	v_add_f32_e32 v38, 1.0, v38
	ds_read_u16 v108, v106
	v_fmamk_f32 v43, v147, 0xbfb8aa3b, v157
	v_fma_f32 v41, -v37, v37, 1.0
	v_max_f32_e32 v41, 0, v41
	s_waitcnt lgkmcnt(0)
	v_lshlrev_b32_e32 v108, 16, v108
	v_sqrt_f32_e32 v41, v41
	s_nop 0
	v_mul_f32_e32 v40, v40, v108
	ds_read_u16 v108, v106 offset:272
	v_exp_f32_e32 v43, v43
	s_waitcnt lgkmcnt(0)
	v_lshlrev_b32_e32 v108, 16, v108
	v_fmamk_f32 v39, v151, 0xbfb8aa3b, v127
	s_waitcnt lgkmcnt(0)
	v_mfma_f32_16x16x32_bf16 v[144:147], v[128:131], v[0:3], 0
	v_mfma_f32_16x16x32_bf16 v[148:151], v[128:131], v[20:23], 0
	v_mfma_f32_16x16x32_bf16 v[144:147], v[132:135], v[4:7], v[144:147]
	v_mfma_f32_16x16x32_bf16 v[148:151], v[132:135], v[24:27], v[148:151]
	v_mfma_f32_16x16x32_bf16 v[144:147], v[136:139], v[12:15], v[144:147]
	v_mfma_f32_16x16x32_bf16 v[148:151], v[136:139], v[28:31], v[148:151]
	v_mfma_f32_16x16x32_bf16 v[144:147], v[140:143], v[16:19], v[144:147]
	v_mfma_f32_16x16x32_bf16 v[148:151], v[140:143], v[32:35], v[148:151]
	v_add_f32_e32 v43, 1.0, v43
	v_mul_f32_e32 v41, v109, v41
	v_rcp_f32_e32 v109, v38
	v_mul_f32_e32 v38, v42, v153
	v_exp_f32_e32 v38, v38
	v_mul_f32_e32 v41, v41, v108
	ds_read_u16 v108, v106 offset:544
	v_exp_f32_e32 v39, v39
	v_fma_f32 v42, -v38, v38, 1.0
	v_max_f32_e32 v42, 0, v42
	v_rcp_f32_e32 v43, v43
	v_sqrt_f32_e32 v42, v42
	s_nop 0
	s_waitcnt lgkmcnt(0)
	v_lshlrev_b32_e32 v108, 16, v108
	v_add_f32_e32 v39, 1.0, v39
	ds_read_u16 v106, v106 offset:816
	s_waitcnt lgkmcnt(0)
	v_lshlrev_b32_e32 v106, 16, v106
	s_nop 1
	s_nop 1
	v_mul_f32_e32 v42, v109, v42
	v_mul_f32_e32 v42, v42, v108
	v_rcp_f32_e32 v108, v39
	v_mul_f32_e32 v39, v43, v153
	v_exp_f32_e32 v39, v39
	s_nop 0
	v_fma_f32 v43, -v39, v39, 1.0
	v_max_f32_e32 v43, 0, v43
	s_nop 0
	v_sqrt_f32_e32 v43, v43
	s_nop 0
	s_nop 0
	s_nop 0
	s_nop 1
	s_nop 1
	v_mul_f32_e32 v43, v108, v43
	v_mul_f32_e32 v43, v43, v106
	s_and_b64 vcc, exec, s[8:9]
	s_cbranch_vccnz .LBB0_167
	v_fma_f32 v108, v38, v43, v42
	v_mul_f32_e32 v109, v38, v39
	v_fma_f32 v111, v37, v108, v41
	v_mul_f32_e32 v110, v37, v109
	v_fma_f32 v112, v36, v111, v40
	v_mul_f32_e32 v106, v36, v110
	s_mov_b64 s[2:3], 0

; __device__ __forceinline__ float bf2f(bf16_t b) { return __uint_as_float(((unsigned)b) << 16); }
; __device__ __forceinline__ float sigmoidf(float z) { return __builtin_amdgcn_rcpf(1.0f + __expf(-z)); }
; __device__ void lru_fused_phase(const int bid, const int nblk, bf16_t* __restrict__ U, bf16_t* __restrict__ HF, const bf16_t* __restrict__ Wg, const float* __restrict__ cw, const float* __restrict__ cb, ...
;     ...
;                     for (int s = 0; s < 4; ++s) {
;                         const bf16x8 af = *(const bf16x8*)(buf + (16 * rt + fr) * RS + (32 * s + 8 * fq) * 2);
;                         za = __builtin_amdgcn_mfma_f32_16x16x32_bf16(af, Bf[0][s], za, 0, 0, 0);
;                         zi = __builtin_amdgcn_mfma_f32_16x16x32_bf16(af, Bf[1][s], zi, 0, 0, 0);
;                     }
;                     float av[4], bv[4];
; #pragma unroll
;                     for (int j = 0; j < 4; ++j) {
;                         const float c = bf2f(*(const unsigned short*)(buf + (16 * rt + 4 * fq + j) * RS + chl * 2));
;                         const float r = sigmoidf(za[j] + ba), ig = sigmoidf(zi[j] + bi_);
;                         const float la = -sp * r;
;                         av[j] = __expf(la);
;                         bv[j] = __builtin_sqrtf(fmaxf(1.0f - av[j] * av[j], 0.f)) * ig * c;
;                     }
.LBB0_188:
	s_mov_b64 s[2:3], -1
	s_waitcnt lgkmcnt(1)
	s_waitcnt lgkmcnt(0)
	s_waitcnt lgkmcnt(0)
	v_or_b32_e32 v104, s38, v46
	v_mad_u32_u24 v104, v104, s35, v10
	ds_read_u16 v10, v104
	s_waitcnt lgkmcnt(1)
	s_waitcnt lgkmcnt(0)
	v_lshlrev_b32_e32 v105, 16, v10
	s_nop 5
	v_fmamk_f32 v10, v144, 0xbfb8aa3b, v157
	v_exp_f32_e32 v10, v10
	v_fmamk_f32 v41, v145, 0xbfb8aa3b, v157
	v_add_f32_e32 v10, 1.0, v10
	v_rcp_f32_e32 v10, v10
	v_exp_f32_e32 v41, v41
	s_nop 2
	v_fmamk_f32 v36, v148, 0xbfb8aa3b, v127
	v_mul_f32_e32 v10, v10, v153
	v_exp_f32_e32 v10, v10
	v_exp_f32_e32 v36, v36
	v_fmamk_f32 v37, v149, 0xbfb8aa3b, v127
	v_fma_f32 v40, -v10, v10, 1.0
	v_max_f32_e32 v40, 0, v40
	v_add_f32_e32 v36, 1.0, v36
	v_sqrt_f32_e32 v40, v40
	s_nop 0
	v_rcp_f32_e32 v36, v36
	v_add_f32_e32 v41, 1.0, v41
	v_exp_f32_e32 v37, v37
	v_rcp_f32_e32 v41, v41
	v_add_f32_e32 v37, 1.0, v37
	v_fmamk_f32 v42, v146, 0xbfb8aa3b, v157
	v_exp_f32_e32 v42, v42
	v_mul_f32_e32 v36, v36, v40
	v_mul_f32_e32 v36, v36, v105
	v_rcp_f32_e32 v105, v37
	v_mul_f32_e32 v37, v41, v153
	v_exp_f32_e32 v37, v37
	v_fmamk_f32 v38, v150, 0xbfb8aa3b, v127
	v_add_f32_e32 v42, 1.0, v42
	v_fma_f32 v41, -v37, v37, 1.0
	v_max_f32_e32 v41, 0, v41
	v_exp_f32_e32 v38, v38
	v_sqrt_f32_e32 v41, v41
	s_nop 0
	v_rcp_f32_e32 v42, v42
	v_add_f32_e32 v38, 1.0, v38
	ds_read_u16 v40, v104 offset:272
	v_fmamk_f32 v43, v147, 0xbfb8aa3b, v157
	v_exp_f32_e32 v43, v43
	s_waitcnt lgkmcnt(0)
	v_lshlrev_b32_e32 v40, 16, v40
	v_fmamk_f32 v39, v151, 0xbfb8aa3b, v127
	v_mul_f32_e32 v41, v105, v41
	v_rcp_f32_e32 v105, v38
	v_mul_f32_e32 v38, v42, v153
	v_exp_f32_e32 v38, v38
	v_mul_f32_e32 v40, v41, v40
	ds_read_u16 v41, v104 offset:544
	v_fma_f32 v42, -v38, v38, 1.0
	v_max_f32_e32 v42, 0, v42
	v_add_f32_e32 v43, 1.0, v43
	v_sqrt_f32_e32 v42, v42
	s_nop 0
	v_exp_f32_e32 v39, v39
	v_rcp_f32_e32 v43, v43
	s_waitcnt lgkmcnt(0)
	v_lshlrev_b32_e32 v41, 16, v41
	v_add_f32_e32 v39, 1.0, v39
	s_nop 1
	s_nop 1
	v_mul_f32_e32 v42, v105, v42
	v_mul_f32_e32 v41, v42, v41
	ds_read_u16 v42, v104 offset:816
	v_rcp_f32_e32 v104, v39
	v_mul_f32_e32 v39, v43, v153
	v_exp_f32_e32 v39, v39
	s_waitcnt lgkmcnt(0)
	v_lshlrev_b32_e32 v42, 16, v42
	v_fma_f32 v43, -v39, v39, 1.0
	v_max_f32_e32 v43, 0, v43
	s_nop 0
	v_sqrt_f32_e32 v43, v43
	s_nop 0
	s_nop 0
	s_nop 0
	s_nop 1
	s_nop 1
	v_mul_f32_e32 v43, v104, v43
	v_mul_f32_e32 v42, v43, v42
	s_and_b64 vcc, exec, s[8:9]
	s_cbranch_vccnz .LBB0_190
	v_fma_f32 v43, v38, v42, v41
	v_mul_f32_e32 v104, v38, v39
	v_fma_f32 v108, v37, v43, v40
	v_mul_f32_e32 v107, v37, v104
	v_fma_f32 v109, v10, v108, v36
	v_mul_f32_e32 v105, v10, v107
	s_mov_b64 s[2:3], 0
